# attention: the 12 Q-fragment staging loads of a unit issued together behind one wait (was load-wait-ds_write x12)
# speedup vs baseline: 1.0031x; 1.0031x over previous
; #define LAS __attribute__((address_space(3)))
; template <int NQB> ...
;     ...
;     LAS bf16x8* qlds = (LAS bf16x8*)((LAS unsigned char*)red + 4096 + h * 12288) + lane;
; #pragma unroll
;     for (int qb = 0; qb < NQB; ++qb)
; #pragma unroll
;         for (int s = 0; s < 6; ++s) qlds[(qb * 6 + s) * 64] = *(const bf16x8*)(Q + (size_t)(qrow0 + 32 * qb + r) * 768 + h * 96 + 16 * s + 8 * hh);
;     f32x16 O[NQB][2]; float mrun[NQB], lrun[NQB];
; #pragma unroll
;     for (int qb = 0; qb < NQB; ++qb) { mrun[qb] = -1e30f; lrun[qb] = 0.f;
; #pragma unroll
;         for (int db = 0; db < 2; ++db)
; #pragma unroll
;             for (int i = 0; i < 16; ++i) O[qb][db][i] = 0.f; }
;     const int pr = (r & 0x13) | ((r & 4) << 1) | ((r & 8) >> 1);
;     const int blk0 = kvrow0 >> 5; (void)pr;
;     const bf16_t* kp = Kn + ((size_t)(blk0 * 8 + h) * 256 + lane) * 8;
;     const bf16_t* krp = Kr + ((size_t)blk0 * 128 + lane) * 8;
;     const bf16_t* vp = VT + ((size_t)(blk0 * 8 + h) * 256 + lane) * 8;
;     bf16x8 Kf[6];
; #pragma unroll
;     for (int s = 0; s < 4; ++s) Kf[s] = *(const bf16x8*)(kp + 512 * s);
;     Kf[4] = *(const bf16x8*)(krp); Kf[5] = *(const bf16x8*)(krp + 512);
.LBB0_83:
	s_or_b64 exec, exec, s[4:5]
	s_waitcnt lgkmcnt(0)
	s_barrier
	ds_read_b32 v0, v133 offset:2048
	s_movk_i32 s1, 0x80
	s_mov_b64 s[4:5], -1
	s_waitcnt lgkmcnt(0)
	s_barrier
	v_cmp_lt_i32_e32 vcc, s1, v0
	v_readfirstlane_b32 s0, v0
	s_cbranch_vccnz .LBB0_78
	s_mul_i32 s1, s81, 0x3000
	s_cmp_lg_u32 s0, 0
	v_add_u32_e32 v194, s1, v129
	s_cbranch_scc0 .LBB0_92
	s_add_i32 s0, s0, -1
	s_ashr_i32 s20, s0, 2
	s_and_b32 s1, s20, -8
	s_or_b32 s4, s1, s58
	s_and_b32 s0, s0, 31
	s_lshl_b32 s1, s4, 11
	s_lshl_b32 s5, s0, 6
	s_or_b32 s1, s1, s5
	v_bitop3_b32 v162, s1, v182, v169 bitop3:0x36
	s_lshl_b32 s21, s0, 1
	v_or_b32_e32 v6, s1, v169
	v_mad_i64_i32 v[4:5], s[0:1], v162, s78, v[126:127]
	global_load_dwordx4 v[8:11], v[4:5], off
	v_bitop3_b32 v160, v6, 32, v182 bitop3:0xde
	v_ashrrev_i32_e32 v163, 31, v162
	v_ashrrev_i32_e32 v161, 31, v160
	v_mov_b32_e32 v195, 0xf149f2ca
	s_mov_b64 s[44:45], 0
	v_mov_b32_e32 v196, 0xf149f2ca
	global_load_dwordx4 v[12:15], v[4:5], off offset:32
	global_load_dwordx4 v[16:19], v[4:5], off offset:64
	global_load_dwordx4 v[20:23], v[4:5], off offset:96
	global_load_dwordx4 v[24:27], v[4:5], off offset:128
	global_load_dwordx4 v[28:31], v[4:5], off offset:160
	v_mad_i64_i32 v[4:5], s[0:1], v160, s78, v[126:127]
	s_lshl_b32 s1, s4, 9
	s_lshl_b32 s0, s4, 6
	s_add_i32 s4, s1, s81
	s_ashr_i32 s5, s4, 31
	s_lshl_b64 s[4:5], s[4:5], 11
	v_mov_b32_e32 v167, s5
	v_or_b32_e32 v166, s4, v128
	s_ashr_i32 s1, s0, 31
	s_lshl_b64 s[0:1], s[0:1], 11
	global_load_dwordx4 v[32:35], v[4:5], off
	global_load_dwordx4 v[36:39], v[4:5], off offset:32
	global_load_dwordx4 v[40:43], v[4:5], off offset:64
	global_load_dwordx4 v[44:47], v[4:5], off offset:96
	global_load_dwordx4 v[48:51], v[4:5], off offset:128
	global_load_dwordx4 v[52:55], v[4:5], off offset:160
	s_waitcnt vmcnt(0)
	ds_write_b128 v194, v[8:11] offset:4096
	ds_write_b128 v194, v[12:15] offset:5120
	ds_write_b128 v194, v[16:19] offset:6144
	ds_write_b128 v194, v[20:23] offset:7168
	ds_write_b128 v194, v[24:27] offset:8192
	ds_write_b128 v194, v[28:31] offset:9216
	ds_write_b128 v194, v[32:35] offset:10240
	ds_write_b128 v194, v[36:39] offset:11264
	ds_write_b128 v194, v[40:43] offset:12288
	ds_write_b128 v194, v[44:47] offset:13312
	ds_write_b128 v194, v[48:51] offset:14336
	ds_write_b128 v194, v[52:55] offset:15360
	v_lshl_add_u64 v[0:1], v[166:167], 1, s[34:35]
	v_lshl_add_u64 v[2:3], v[130:131], 0, s[0:1]
	global_load_dwordx4 v[116:119], v[0:1], off
	global_load_dwordx4 v[112:115], v[0:1], off offset:1024
	global_load_dwordx4 v[108:111], v[0:1], off offset:2048
	global_load_dwordx4 v[104:107], v[0:1], off offset:3072
	global_load_dwordx4 v[100:103], v[2:3], off
	global_load_dwordx4 v[96:99], v[2:3], off offset:1024
	s_lshr_b32 s1, s20, 3
	s_lshl_b32 s4, s1, 9
	s_or_b32 s4, s47, s4
	s_ashr_i32 s5, s4, 31
	s_xor_b32 s0, s21, 63
	s_lshl_b64 s[4:5], s[4:5], 11
	s_add_u32 s4, s54, s4
	s_addc_u32 s5, s55, s5
	s_lshl_b32 s1, s1, 12
	s_add_i32 s20, s59, s1
	s_ashr_i32 s21, s20, 31
	s_lshl_b64 s[20:21], s[20:21], 12
	s_add_u32 s20, s54, s20
	v_mov_b32_e32 v0, 0
	s_addc_u32 s21, s55, s21
	v_mov_b32_e32 v1, v0
	v_mov_b32_e32 v2, v0
	v_mov_b32_e32 v3, v0
	v_mov_b32_e32 v4, v0
	v_mov_b32_e32 v5, v0
	v_mov_b32_e32 v6, v0
	v_mov_b32_e32 v7, v0
	v_mov_b32_e32 v8, v0
	v_mov_b32_e32 v9, v0
	v_mov_b32_e32 v10, v0
	v_mov_b32_e32 v11, v0
	v_mov_b32_e32 v12, v0
	v_mov_b32_e32 v13, v0
	v_mov_b32_e32 v14, v0
	v_mov_b32_e32 v15, v0
	v_mov_b32_e32 v16, v0
	v_mov_b32_e32 v17, v0
	v_mov_b32_e32 v18, v0
	v_mov_b32_e32 v19, v0
	v_mov_b32_e32 v20, v0
	v_mov_b32_e32 v21, v0
	v_mov_b32_e32 v22, v0
	v_mov_b32_e32 v23, v0
	v_mov_b32_e32 v24, v0
	v_mov_b32_e32 v25, v0
	v_mov_b32_e32 v26, v0
	v_mov_b32_e32 v27, v0
	v_mov_b32_e32 v28, v0
	v_mov_b32_e32 v29, v0
	v_mov_b32_e32 v30, v0
	v_mov_b32_e32 v31, v0
	v_mov_b32_e32 v32, v0
	v_mov_b32_e32 v33, v0
	v_mov_b32_e32 v34, v0
	v_mov_b32_e32 v35, v0
	v_mov_b32_e32 v36, v0
	v_mov_b32_e32 v37, v0
	v_mov_b32_e32 v38, v0
	v_mov_b32_e32 v39, v0
	v_mov_b32_e32 v40, v0
	v_mov_b32_e32 v41, v0
	v_mov_b32_e32 v42, v0
	v_mov_b32_e32 v43, v0
	v_mov_b32_e32 v44, v0
	v_mov_b32_e32 v45, v0
	v_mov_b32_e32 v46, v0
	v_mov_b32_e32 v47, v0
	v_mov_b32_e32 v48, v0
	v_mov_b32_e32 v49, v0
	v_mov_b32_e32 v50, v0
	v_mov_b32_e32 v51, v0
	v_mov_b32_e32 v52, v0
	v_mov_b32_e32 v53, v0
	v_mov_b32_e32 v54, v0
	v_mov_b32_e32 v55, v0
	v_mov_b32_e32 v56, v0
	v_mov_b32_e32 v57, v0
	v_mov_b32_e32 v58, v0
	v_mov_b32_e32 v59, v0
	v_mov_b32_e32 v60, v0
	v_mov_b32_e32 v61, v0
	v_mov_b32_e32 v62, v0
	v_mov_b32_e32 v63, v0
	v_mov_b32_e32 v164, v0
	v_mov_b32_e32 v165, v0
